# layer-0 pool phase: rstd-table rows (6 per wave, 48 loads) issued together with interleaved wave reductions
# speedup vs baseline: 1.0220x; 1.0028x over previous
; __device__ __forceinline__ float rstd_of(float ssq) { return __builtin_amdgcn_rsqf(ssq * (1.0f / DM) + RMS_EPS); }
; __device__ __forceinline__ void pool_phase(const float* __restrict__ x, const bf16_t* __restrict__ x16, const float* __restrict__ g, const float* rsq, bf16_t* __restrict__ pooled, LAS unsigned char* lds, int tid, int wid, int lane, int bid) {
;     ...
;         for (int i = wid; i < 47; i += NWAVE) { const int r = t0 - 15 + i; float val = 0.f;
;             if (r >= bstart && rsq) val = rstd_of(wave_sum(lane < 32 ? rsq[(size_t)r * 64 + lane] : 0.f));
;             else if (r >= bstart) { float s = 0.f; const f32x4* xr = (const f32x4*)(x + (size_t)r * DM);
; #pragma unroll
;                 for (int j = 0; j < 8; ++j) { const f32x4 v = xr[lane + 64 * j]; s += (v[0] * v[0] + v[1] * v[1]) + (v[2] * v[2] + v[3] * v[3]); }
;                 val = 1.0f / sqrtf(wave_sum(s) * (1.0f / DM) + RMS_EPS); }
;             if (lane == 0) rs[i] = val; }
.LBB0_70:
	s_ashr_i32 s12, s3, 31
	s_lshr_b32 s12, s12, 26
	s_add_i32 s12, s3, s12
	s_lshl_b32 s12, s12, 5
	s_and_b64 vcc, exec, s[10:11]
	s_and_b32 s44, s12, 0xfffff800
	s_cbranch_vccnz .LBB0_77
	s_mov_b32 s13, 0
	v_lshlrev_b32_e32 v77, 2, v31
	v_lshlrev_b32_e32 v78, 2, v32
	v_lshlrev_b32_e32 v79, 2, v33
	v_lshlrev_b32_e32 v82, 2, v34
	v_lshlrev_b32_e32 v83, 2, v35
	v_lshlrev_b32_e32 v206, 2, v36
	s_add_i32 s15, s16, 0
	s_max_i32 s15, s15, s44
	s_min_i32 s15, s15, 0x1fff
	s_lshl_b32 s12, s15, 13
	v_lshl_add_u64 v[66:67], v[14:15], 0, s[12:13]
	global_load_dwordx4 v[18:21], v[66:67], off offset:-4096
	global_load_dwordx4 v[38:41], v[66:67], off offset:-3072
	global_load_dwordx4 v[42:45], v[66:67], off offset:-2048
	global_load_dwordx4 v[46:49], v[66:67], off
	global_load_dwordx4 v[50:53], v[66:67], off offset:-1024
	global_load_dwordx4 v[54:57], v[66:67], off offset:1024
	global_load_dwordx4 v[58:61], v[66:67], off offset:3072
	global_load_dwordx4 v[62:65], v[66:67], off offset:2048
	s_add_i32 s15, s16, 8
	s_max_i32 s15, s15, s44
	s_min_i32 s15, s15, 0x1fff
	s_lshl_b32 s12, s15, 13
	v_lshl_add_u64 v[66:67], v[14:15], 0, s[12:13]
	global_load_dwordx4 v[84:87], v[66:67], off offset:-4096
	global_load_dwordx4 v[88:91], v[66:67], off offset:-3072
	global_load_dwordx4 v[92:95], v[66:67], off offset:-2048
	global_load_dwordx4 v[96:99], v[66:67], off
	global_load_dwordx4 v[100:103], v[66:67], off offset:-1024
	global_load_dwordx4 v[104:107], v[66:67], off offset:1024
	global_load_dwordx4 v[108:111], v[66:67], off offset:3072
	global_load_dwordx4 v[112:115], v[66:67], off offset:2048
	s_add_i32 s15, s16, 16
	s_max_i32 s15, s15, s44
	s_min_i32 s15, s15, 0x1fff
	s_lshl_b32 s12, s15, 13
	v_lshl_add_u64 v[66:67], v[14:15], 0, s[12:13]
	global_load_dwordx4 v[116:119], v[66:67], off offset:-4096
	global_load_dwordx4 v[120:123], v[66:67], off offset:-3072
	global_load_dwordx4 v[124:127], v[66:67], off offset:-2048
	global_load_dwordx4 v[128:131], v[66:67], off
	global_load_dwordx4 v[132:135], v[66:67], off offset:-1024
	global_load_dwordx4 v[136:139], v[66:67], off offset:1024
	global_load_dwordx4 v[140:143], v[66:67], off offset:3072
	global_load_dwordx4 v[144:147], v[66:67], off offset:2048
	s_add_i32 s15, s16, 24
	s_max_i32 s15, s15, s44
	s_min_i32 s15, s15, 0x1fff
	s_lshl_b32 s12, s15, 13
	v_lshl_add_u64 v[66:67], v[14:15], 0, s[12:13]
	global_load_dwordx4 v[148:151], v[66:67], off offset:-4096
	global_load_dwordx4 v[152:155], v[66:67], off offset:-3072
	global_load_dwordx4 v[156:159], v[66:67], off offset:-2048
	global_load_dwordx4 v[160:163], v[66:67], off
	global_load_dwordx4 v[164:167], v[66:67], off offset:-1024
	global_load_dwordx4 v[168:171], v[66:67], off offset:1024
	global_load_dwordx4 v[172:175], v[66:67], off offset:3072
	global_load_dwordx4 v[176:179], v[66:67], off offset:2048
	s_add_i32 s15, s16, 32
	s_max_i32 s15, s15, s44
	s_min_i32 s15, s15, 0x1fff
	s_lshl_b32 s12, s15, 13
	v_lshl_add_u64 v[66:67], v[14:15], 0, s[12:13]
	global_load_dwordx4 v[180:183], v[66:67], off offset:-4096
	global_load_dwordx4 v[184:187], v[66:67], off offset:-3072
	global_load_dwordx4 v[188:191], v[66:67], off offset:-2048
	global_load_dwordx4 v[192:195], v[66:67], off
	global_load_dwordx4 v[196:199], v[66:67], off offset:-1024
	global_load_dwordx4 v[200:203], v[66:67], off offset:1024
	global_load_dwordx4 v[208:211], v[66:67], off offset:3072
	global_load_dwordx4 v[212:215], v[66:67], off offset:2048
	s_add_i32 s15, s16, 40
	s_max_i32 s15, s15, s44
	s_min_i32 s15, s15, 0x1fff
	s_lshl_b32 s12, s15, 13
	v_lshl_add_u64 v[66:67], v[14:15], 0, s[12:13]
	global_load_dwordx4 v[216:219], v[66:67], off offset:-4096
	global_load_dwordx4 v[220:223], v[66:67], off offset:-3072
	global_load_dwordx4 v[224:227], v[66:67], off offset:-2048
	global_load_dwordx4 v[228:231], v[66:67], off
	global_load_dwordx4 v[232:235], v[66:67], off offset:-1024
	global_load_dwordx4 v[236:239], v[66:67], off offset:1024
	global_load_dwordx4 v[240:243], v[66:67], off offset:3072
	global_load_dwordx4 v[244:247], v[66:67], off offset:2048
	s_waitcnt vmcnt(40)
	v_mov_b32_e32 v8, v18
	v_mov_b32_e32 v9, v38
	v_mov_b32_e32 v38, v19
	v_mov_b32_e32 v19, v40
	v_mov_b32_e32 v40, v21
	v_mov_b32_e32 v18, v20
	v_pk_mul_f32 v[20:21], v[44:45], v[44:45]
	v_pk_mul_f32 v[42:43], v[42:43], v[42:43]
	v_pk_mul_f32 v[38:39], v[38:39], v[38:39]
	v_pk_mul_f32 v[40:41], v[40:41], v[40:41]
	v_mul_f32_e32 v69, v60, v60
	v_mul_f32_e32 v70, v61, v61
	v_pk_mov_b32 v[60:61], v[42:43], v[20:21] op_sel:[1,0]
	v_mov_b32_e32 v43, v21
	v_pk_fma_f32 v[8:9], v[8:9], v[8:9], v[38:39]
	v_pk_fma_f32 v[18:19], v[18:19], v[18:19], v[40:41]
	v_mul_f32_e32 v37, v46, v46
	v_mul_f32_e32 v44, v51, v51
	v_mul_f32_e32 v46, v53, v53
	v_pk_add_f32 v[38:39], v[60:61], v[42:43]
	v_pk_add_f32 v[8:9], v[8:9], v[18:19]
	v_mul_f32_e32 v66, v47, v47
	v_mul_f32_e32 v67, v48, v48
	v_mul_f32_e32 v68, v49, v49
	v_pk_fma_f32 v[20:21], v[50:51], v[50:51], v[44:45] op_sel_hi:[1,1,0]
	v_pk_fma_f32 v[44:45], v[52:53], v[52:53], v[46:47] op_sel_hi:[1,1,0]
	v_pk_add_f32 v[18:19], v[38:39], v[38:39] op_sel:[0,1] op_sel_hi:[1,0]
	v_pk_add_f32 v[8:9], v[8:9], v[8:9] op_sel:[0,1] op_sel_hi:[1,0]
	v_pk_mul_f32 v[48:49], v[56:57], v[56:57]
	v_pk_mul_f32 v[54:55], v[54:55], v[54:55]
	v_mov_b32_e32 v21, v67
	v_mov_b32_e32 v45, v68
	v_mov_b32_e32 v19, v66
	v_mov_b32_e32 v9, v37
	v_pk_mov_b32 v[46:47], v[54:55], v[48:49] op_sel:[1,0]
	v_mov_b32_e32 v55, v49
	v_pk_add_f32 v[20:21], v[20:21], v[44:45]
	v_pk_add_f32 v[8:9], v[8:9], v[18:19]
	v_mul_f32_e32 v57, v58, v58
	v_mul_f32_e32 v59, v59, v59
	v_mul_f32_e32 v56, v63, v63
	v_mul_f32_e32 v58, v65, v65
	v_pk_add_f32 v[40:41], v[46:47], v[54:55]
	v_pk_add_f32 v[8:9], v[8:9], v[20:21]
	v_pk_fma_f32 v[48:49], v[62:63], v[62:63], v[56:57] op_sel_hi:[1,1,0]
	v_pk_fma_f32 v[50:51], v[64:65], v[64:65], v[58:59] op_sel_hi:[1,1,0]
	v_pk_add_f32 v[38:39], v[40:41], v[40:41] op_sel:[0,1] op_sel_hi:[1,0]
	v_pk_add_f32 v[8:9], v[8:9], v[8:9] op_sel:[0,1] op_sel_hi:[1,0]
	v_mov_b32_e32 v49, v69
	v_mov_b32_e32 v51, v70
	v_mov_b32_e32 v39, v59
	v_mov_b32_e32 v9, v57
	v_pk_add_f32 v[40:41], v[48:49], v[50:51]
	v_pk_add_f32 v[8:9], v[8:9], v[38:39]
	v_pk_add_f32 v[8:9], v[8:9], v[40:41]
	v_add_f32_e32 v8, v8, v9
	v_mov_b32_e32 v71, v8
	s_waitcnt vmcnt(32)
; __device__ __forceinline__ void pool_phase(const float* __restrict__ x, const bf16_t* __restrict__ x16, const float* __restrict__ g, const float* rsq, bf16_t* __restrict__ pooled, LAS unsigned char* lds, int tid, int wid, int lane, int bid) {
;     ...
;             else if (r >= bstart) { float s = 0.f; const f32x4* xr = (const f32x4*)(x + (size_t)r * DM);
; #pragma unroll
;                 for (int j = 0; j < 8; ++j) { const f32x4 v = xr[lane + 64 * j]; s += (v[0] * v[0] + v[1] * v[1]) + (v[2] * v[2] + v[3] * v[3]); }
;                 val = 1.0f / sqrtf(wave_sum(s) * (1.0f / DM) + RMS_EPS); }
	v_mov_b32_e32 v18, v84
	v_mov_b32_e32 v19, v85
	v_mov_b32_e32 v20, v86
	v_mov_b32_e32 v21, v87
	v_mov_b32_e32 v38, v88
	v_mov_b32_e32 v39, v89
	v_mov_b32_e32 v40, v90
	v_mov_b32_e32 v41, v91
	v_mov_b32_e32 v42, v92
	v_mov_b32_e32 v43, v93
	v_mov_b32_e32 v44, v94
	v_mov_b32_e32 v45, v95
	v_mov_b32_e32 v46, v96
	v_mov_b32_e32 v47, v97
	v_mov_b32_e32 v48, v98
	v_mov_b32_e32 v49, v99
	v_mov_b32_e32 v50, v100
	v_mov_b32_e32 v51, v101
	v_mov_b32_e32 v52, v102
	v_mov_b32_e32 v53, v103
	v_mov_b32_e32 v54, v104
	v_mov_b32_e32 v55, v105
	v_mov_b32_e32 v56, v106
	v_mov_b32_e32 v57, v107
	v_mov_b32_e32 v58, v108
	v_mov_b32_e32 v59, v109
	v_mov_b32_e32 v60, v110
	v_mov_b32_e32 v61, v111
	v_mov_b32_e32 v62, v112
	v_mov_b32_e32 v63, v113
	v_mov_b32_e32 v64, v114
	v_mov_b32_e32 v65, v115
	v_mov_b32_e32 v8, v18
	v_mov_b32_e32 v9, v38
	v_mov_b32_e32 v38, v19
	v_mov_b32_e32 v19, v40
	v_mov_b32_e32 v40, v21
	v_mov_b32_e32 v18, v20
	v_pk_mul_f32 v[20:21], v[44:45], v[44:45]
	v_pk_mul_f32 v[42:43], v[42:43], v[42:43]
	v_pk_mul_f32 v[38:39], v[38:39], v[38:39]
	v_pk_mul_f32 v[40:41], v[40:41], v[40:41]
	v_mul_f32_e32 v69, v60, v60
	v_mul_f32_e32 v70, v61, v61
	v_pk_mov_b32 v[60:61], v[42:43], v[20:21] op_sel:[1,0]
	v_mov_b32_e32 v43, v21
	v_pk_fma_f32 v[8:9], v[8:9], v[8:9], v[38:39]
	v_pk_fma_f32 v[18:19], v[18:19], v[18:19], v[40:41]
	v_mul_f32_e32 v37, v46, v46
	v_mul_f32_e32 v44, v51, v51
	v_mul_f32_e32 v46, v53, v53
	v_pk_add_f32 v[38:39], v[60:61], v[42:43]
	v_pk_add_f32 v[8:9], v[8:9], v[18:19]
	v_mul_f32_e32 v66, v47, v47
	v_mul_f32_e32 v67, v48, v48
	v_mul_f32_e32 v68, v49, v49
	v_pk_fma_f32 v[20:21], v[50:51], v[50:51], v[44:45] op_sel_hi:[1,1,0]
	v_pk_fma_f32 v[44:45], v[52:53], v[52:53], v[46:47] op_sel_hi:[1,1,0]
	v_pk_add_f32 v[18:19], v[38:39], v[38:39] op_sel:[0,1] op_sel_hi:[1,0]
	v_pk_add_f32 v[8:9], v[8:9], v[8:9] op_sel:[0,1] op_sel_hi:[1,0]
	v_pk_mul_f32 v[48:49], v[56:57], v[56:57]
	v_pk_mul_f32 v[54:55], v[54:55], v[54:55]
	v_mov_b32_e32 v21, v67
	v_mov_b32_e32 v45, v68
	v_mov_b32_e32 v19, v66
	v_mov_b32_e32 v9, v37
	v_pk_mov_b32 v[46:47], v[54:55], v[48:49] op_sel:[1,0]
	v_mov_b32_e32 v55, v49
	v_pk_add_f32 v[20:21], v[20:21], v[44:45]
	v_pk_add_f32 v[8:9], v[8:9], v[18:19]
	v_mul_f32_e32 v57, v58, v58
	v_mul_f32_e32 v59, v59, v59
	v_mul_f32_e32 v56, v63, v63
	v_mul_f32_e32 v58, v65, v65
	v_pk_add_f32 v[40:41], v[46:47], v[54:55]
	v_pk_add_f32 v[8:9], v[8:9], v[20:21]
	v_pk_fma_f32 v[48:49], v[62:63], v[62:63], v[56:57] op_sel_hi:[1,1,0]
	v_pk_fma_f32 v[50:51], v[64:65], v[64:65], v[58:59] op_sel_hi:[1,1,0]
	v_pk_add_f32 v[38:39], v[40:41], v[40:41] op_sel:[0,1] op_sel_hi:[1,0]
	v_pk_add_f32 v[8:9], v[8:9], v[8:9] op_sel:[0,1] op_sel_hi:[1,0]
	v_mov_b32_e32 v49, v69
	v_mov_b32_e32 v51, v70
	v_mov_b32_e32 v39, v59
	v_mov_b32_e32 v9, v57
	v_pk_add_f32 v[40:41], v[48:49], v[50:51]
	v_pk_add_f32 v[8:9], v[8:9], v[38:39]
	v_pk_add_f32 v[8:9], v[8:9], v[40:41]
	v_add_f32_e32 v8, v8, v9
	v_mov_b32_e32 v72, v8
	s_waitcnt vmcnt(24)
	v_mov_b32_e32 v18, v116
	v_mov_b32_e32 v19, v117
	v_mov_b32_e32 v20, v118
	v_mov_b32_e32 v21, v119
	v_mov_b32_e32 v38, v120
	v_mov_b32_e32 v39, v121
	v_mov_b32_e32 v40, v122
	v_mov_b32_e32 v41, v123
	v_mov_b32_e32 v42, v124
	v_mov_b32_e32 v43, v125
	v_mov_b32_e32 v44, v126
	v_mov_b32_e32 v45, v127
	v_mov_b32_e32 v46, v128
	v_mov_b32_e32 v47, v129
	v_mov_b32_e32 v48, v130
	v_mov_b32_e32 v49, v131
	v_mov_b32_e32 v50, v132
	v_mov_b32_e32 v51, v133
	v_mov_b32_e32 v52, v134
	v_mov_b32_e32 v53, v135
	v_mov_b32_e32 v54, v136
	v_mov_b32_e32 v55, v137
	v_mov_b32_e32 v56, v138
	v_mov_b32_e32 v57, v139
	v_mov_b32_e32 v58, v140
	v_mov_b32_e32 v59, v141
	v_mov_b32_e32 v60, v142
	v_mov_b32_e32 v61, v143
	v_mov_b32_e32 v62, v144
	v_mov_b32_e32 v63, v145
	v_mov_b32_e32 v64, v146
	v_mov_b32_e32 v65, v147
	v_mov_b32_e32 v8, v18
	v_mov_b32_e32 v9, v38
	v_mov_b32_e32 v38, v19
	v_mov_b32_e32 v19, v40
	v_mov_b32_e32 v40, v21
	v_mov_b32_e32 v18, v20
	v_pk_mul_f32 v[20:21], v[44:45], v[44:45]
	v_pk_mul_f32 v[42:43], v[42:43], v[42:43]
	v_pk_mul_f32 v[38:39], v[38:39], v[38:39]
	v_pk_mul_f32 v[40:41], v[40:41], v[40:41]
	v_mul_f32_e32 v69, v60, v60
	v_mul_f32_e32 v70, v61, v61
	v_pk_mov_b32 v[60:61], v[42:43], v[20:21] op_sel:[1,0]
	v_mov_b32_e32 v43, v21
	v_pk_fma_f32 v[8:9], v[8:9], v[8:9], v[38:39]
	v_pk_fma_f32 v[18:19], v[18:19], v[18:19], v[40:41]
	v_mul_f32_e32 v37, v46, v46
	v_mul_f32_e32 v44, v51, v51
	v_mul_f32_e32 v46, v53, v53
	v_pk_add_f32 v[38:39], v[60:61], v[42:43]
	v_pk_add_f32 v[8:9], v[8:9], v[18:19]
	v_mul_f32_e32 v66, v47, v47
	v_mul_f32_e32 v67, v48, v48
	v_mul_f32_e32 v68, v49, v49
	v_pk_fma_f32 v[20:21], v[50:51], v[50:51], v[44:45] op_sel_hi:[1,1,0]
	v_pk_fma_f32 v[44:45], v[52:53], v[52:53], v[46:47] op_sel_hi:[1,1,0]
	v_pk_add_f32 v[18:19], v[38:39], v[38:39] op_sel:[0,1] op_sel_hi:[1,0]
	v_pk_add_f32 v[8:9], v[8:9], v[8:9] op_sel:[0,1] op_sel_hi:[1,0]
	v_pk_mul_f32 v[48:49], v[56:57], v[56:57]
	v_pk_mul_f32 v[54:55], v[54:55], v[54:55]
	v_mov_b32_e32 v21, v67
	v_mov_b32_e32 v45, v68
	v_mov_b32_e32 v19, v66
	v_mov_b32_e32 v9, v37
	v_pk_mov_b32 v[46:47], v[54:55], v[48:49] op_sel:[1,0]
	v_mov_b32_e32 v55, v49
	v_pk_add_f32 v[20:21], v[20:21], v[44:45]
	v_pk_add_f32 v[8:9], v[8:9], v[18:19]
	v_mul_f32_e32 v57, v58, v58
	v_mul_f32_e32 v59, v59, v59
	v_mul_f32_e32 v56, v63, v63
	v_mul_f32_e32 v58, v65, v65
	v_pk_add_f32 v[40:41], v[46:47], v[54:55]
	v_pk_add_f32 v[8:9], v[8:9], v[20:21]
	v_pk_fma_f32 v[48:49], v[62:63], v[62:63], v[56:57] op_sel_hi:[1,1,0]
	v_pk_fma_f32 v[50:51], v[64:65], v[64:65], v[58:59] op_sel_hi:[1,1,0]
	v_pk_add_f32 v[38:39], v[40:41], v[40:41] op_sel:[0,1] op_sel_hi:[1,0]
	v_pk_add_f32 v[8:9], v[8:9], v[8:9] op_sel:[0,1] op_sel_hi:[1,0]
	v_mov_b32_e32 v49, v69
	v_mov_b32_e32 v51, v70
	v_mov_b32_e32 v39, v59
	v_mov_b32_e32 v9, v57
	v_pk_add_f32 v[40:41], v[48:49], v[50:51]
	v_pk_add_f32 v[8:9], v[8:9], v[38:39]
	v_pk_add_f32 v[8:9], v[8:9], v[40:41]
	v_add_f32_e32 v8, v8, v9
	v_mov_b32_e32 v73, v8
	s_waitcnt vmcnt(16)
; __device__ __forceinline__ void pool_phase(const float* __restrict__ x, const bf16_t* __restrict__ x16, const float* __restrict__ g, const float* rsq, bf16_t* __restrict__ pooled, LAS unsigned char* lds, int tid, int wid, int lane, int bid) {
;     ...
;             else if (r >= bstart) { float s = 0.f; const f32x4* xr = (const f32x4*)(x + (size_t)r * DM);
; #pragma unroll
;                 for (int j = 0; j < 8; ++j) { const f32x4 v = xr[lane + 64 * j]; s += (v[0] * v[0] + v[1] * v[1]) + (v[2] * v[2] + v[3] * v[3]); }
;                 val = 1.0f / sqrtf(wave_sum(s) * (1.0f / DM) + RMS_EPS); }
	v_mov_b32_e32 v18, v148
	v_mov_b32_e32 v19, v149
	v_mov_b32_e32 v20, v150
	v_mov_b32_e32 v21, v151
	v_mov_b32_e32 v38, v152
	v_mov_b32_e32 v39, v153
	v_mov_b32_e32 v40, v154
	v_mov_b32_e32 v41, v155
	v_mov_b32_e32 v42, v156
	v_mov_b32_e32 v43, v157
	v_mov_b32_e32 v44, v158
	v_mov_b32_e32 v45, v159
	v_mov_b32_e32 v46, v160
	v_mov_b32_e32 v47, v161
	v_mov_b32_e32 v48, v162
	v_mov_b32_e32 v49, v163
	v_mov_b32_e32 v50, v164
	v_mov_b32_e32 v51, v165
	v_mov_b32_e32 v52, v166
	v_mov_b32_e32 v53, v167
	v_mov_b32_e32 v54, v168
	v_mov_b32_e32 v55, v169
	v_mov_b32_e32 v56, v170
	v_mov_b32_e32 v57, v171
	v_mov_b32_e32 v58, v172
	v_mov_b32_e32 v59, v173
	v_mov_b32_e32 v60, v174
	v_mov_b32_e32 v61, v175
	v_mov_b32_e32 v62, v176
	v_mov_b32_e32 v63, v177
	v_mov_b32_e32 v64, v178
	v_mov_b32_e32 v65, v179
	v_mov_b32_e32 v8, v18
	v_mov_b32_e32 v9, v38
	v_mov_b32_e32 v38, v19
	v_mov_b32_e32 v19, v40
	v_mov_b32_e32 v40, v21
	v_mov_b32_e32 v18, v20
	v_pk_mul_f32 v[20:21], v[44:45], v[44:45]
	v_pk_mul_f32 v[42:43], v[42:43], v[42:43]
	v_pk_mul_f32 v[38:39], v[38:39], v[38:39]
	v_pk_mul_f32 v[40:41], v[40:41], v[40:41]
	v_mul_f32_e32 v69, v60, v60
	v_mul_f32_e32 v70, v61, v61
	v_pk_mov_b32 v[60:61], v[42:43], v[20:21] op_sel:[1,0]
	v_mov_b32_e32 v43, v21
	v_pk_fma_f32 v[8:9], v[8:9], v[8:9], v[38:39]
	v_pk_fma_f32 v[18:19], v[18:19], v[18:19], v[40:41]
	v_mul_f32_e32 v37, v46, v46
	v_mul_f32_e32 v44, v51, v51
	v_mul_f32_e32 v46, v53, v53
	v_pk_add_f32 v[38:39], v[60:61], v[42:43]
	v_pk_add_f32 v[8:9], v[8:9], v[18:19]
	v_mul_f32_e32 v66, v47, v47
	v_mul_f32_e32 v67, v48, v48
	v_mul_f32_e32 v68, v49, v49
	v_pk_fma_f32 v[20:21], v[50:51], v[50:51], v[44:45] op_sel_hi:[1,1,0]
	v_pk_fma_f32 v[44:45], v[52:53], v[52:53], v[46:47] op_sel_hi:[1,1,0]
	v_pk_add_f32 v[18:19], v[38:39], v[38:39] op_sel:[0,1] op_sel_hi:[1,0]
	v_pk_add_f32 v[8:9], v[8:9], v[8:9] op_sel:[0,1] op_sel_hi:[1,0]
	v_pk_mul_f32 v[48:49], v[56:57], v[56:57]
	v_pk_mul_f32 v[54:55], v[54:55], v[54:55]
	v_mov_b32_e32 v21, v67
	v_mov_b32_e32 v45, v68
	v_mov_b32_e32 v19, v66
	v_mov_b32_e32 v9, v37
	v_pk_mov_b32 v[46:47], v[54:55], v[48:49] op_sel:[1,0]
	v_mov_b32_e32 v55, v49
	v_pk_add_f32 v[20:21], v[20:21], v[44:45]
	v_pk_add_f32 v[8:9], v[8:9], v[18:19]
	v_mul_f32_e32 v57, v58, v58
	v_mul_f32_e32 v59, v59, v59
	v_mul_f32_e32 v56, v63, v63
	v_mul_f32_e32 v58, v65, v65
	v_pk_add_f32 v[40:41], v[46:47], v[54:55]
	v_pk_add_f32 v[8:9], v[8:9], v[20:21]
	v_pk_fma_f32 v[48:49], v[62:63], v[62:63], v[56:57] op_sel_hi:[1,1,0]
	v_pk_fma_f32 v[50:51], v[64:65], v[64:65], v[58:59] op_sel_hi:[1,1,0]
	v_pk_add_f32 v[38:39], v[40:41], v[40:41] op_sel:[0,1] op_sel_hi:[1,0]
	v_pk_add_f32 v[8:9], v[8:9], v[8:9] op_sel:[0,1] op_sel_hi:[1,0]
	v_mov_b32_e32 v49, v69
	v_mov_b32_e32 v51, v70
	v_mov_b32_e32 v39, v59
	v_mov_b32_e32 v9, v57
	v_pk_add_f32 v[40:41], v[48:49], v[50:51]
	v_pk_add_f32 v[8:9], v[8:9], v[38:39]
	v_pk_add_f32 v[8:9], v[8:9], v[40:41]
	v_add_f32_e32 v8, v8, v9
	v_mov_b32_e32 v74, v8
	s_waitcnt vmcnt(8)
	v_mov_b32_e32 v18, v180
	v_mov_b32_e32 v19, v181
	v_mov_b32_e32 v20, v182
	v_mov_b32_e32 v21, v183
	v_mov_b32_e32 v38, v184
	v_mov_b32_e32 v39, v185
	v_mov_b32_e32 v40, v186
	v_mov_b32_e32 v41, v187
	v_mov_b32_e32 v42, v188
	v_mov_b32_e32 v43, v189
	v_mov_b32_e32 v44, v190
	v_mov_b32_e32 v45, v191
	v_mov_b32_e32 v46, v192
	v_mov_b32_e32 v47, v193
	v_mov_b32_e32 v48, v194
	v_mov_b32_e32 v49, v195
	v_mov_b32_e32 v50, v196
	v_mov_b32_e32 v51, v197
	v_mov_b32_e32 v52, v198
	v_mov_b32_e32 v53, v199
	v_mov_b32_e32 v54, v200
	v_mov_b32_e32 v55, v201
	v_mov_b32_e32 v56, v202
	v_mov_b32_e32 v57, v203
	v_mov_b32_e32 v58, v208
	v_mov_b32_e32 v59, v209
	v_mov_b32_e32 v60, v210
	v_mov_b32_e32 v61, v211
	v_mov_b32_e32 v62, v212
	v_mov_b32_e32 v63, v213
	v_mov_b32_e32 v64, v214
	v_mov_b32_e32 v65, v215
	v_mov_b32_e32 v8, v18
	v_mov_b32_e32 v9, v38
	v_mov_b32_e32 v38, v19
	v_mov_b32_e32 v19, v40
	v_mov_b32_e32 v40, v21
	v_mov_b32_e32 v18, v20
	v_pk_mul_f32 v[20:21], v[44:45], v[44:45]
	v_pk_mul_f32 v[42:43], v[42:43], v[42:43]
	v_pk_mul_f32 v[38:39], v[38:39], v[38:39]
	v_pk_mul_f32 v[40:41], v[40:41], v[40:41]
	v_mul_f32_e32 v69, v60, v60
	v_mul_f32_e32 v70, v61, v61
	v_pk_mov_b32 v[60:61], v[42:43], v[20:21] op_sel:[1,0]
	v_mov_b32_e32 v43, v21
	v_pk_fma_f32 v[8:9], v[8:9], v[8:9], v[38:39]
	v_pk_fma_f32 v[18:19], v[18:19], v[18:19], v[40:41]
	v_mul_f32_e32 v37, v46, v46
	v_mul_f32_e32 v44, v51, v51
	v_mul_f32_e32 v46, v53, v53
	v_pk_add_f32 v[38:39], v[60:61], v[42:43]
	v_pk_add_f32 v[8:9], v[8:9], v[18:19]
	v_mul_f32_e32 v66, v47, v47
	v_mul_f32_e32 v67, v48, v48
	v_mul_f32_e32 v68, v49, v49
	v_pk_fma_f32 v[20:21], v[50:51], v[50:51], v[44:45] op_sel_hi:[1,1,0]
	v_pk_fma_f32 v[44:45], v[52:53], v[52:53], v[46:47] op_sel_hi:[1,1,0]
	v_pk_add_f32 v[18:19], v[38:39], v[38:39] op_sel:[0,1] op_sel_hi:[1,0]
	v_pk_add_f32 v[8:9], v[8:9], v[8:9] op_sel:[0,1] op_sel_hi:[1,0]
	v_pk_mul_f32 v[48:49], v[56:57], v[56:57]
	v_pk_mul_f32 v[54:55], v[54:55], v[54:55]
	v_mov_b32_e32 v21, v67
	v_mov_b32_e32 v45, v68
	v_mov_b32_e32 v19, v66
	v_mov_b32_e32 v9, v37
	v_pk_mov_b32 v[46:47], v[54:55], v[48:49] op_sel:[1,0]
	v_mov_b32_e32 v55, v49
	v_pk_add_f32 v[20:21], v[20:21], v[44:45]
	v_pk_add_f32 v[8:9], v[8:9], v[18:19]
	v_mul_f32_e32 v57, v58, v58
	v_mul_f32_e32 v59, v59, v59
	v_mul_f32_e32 v56, v63, v63
	v_mul_f32_e32 v58, v65, v65
	v_pk_add_f32 v[40:41], v[46:47], v[54:55]
	v_pk_add_f32 v[8:9], v[8:9], v[20:21]
	v_pk_fma_f32 v[48:49], v[62:63], v[62:63], v[56:57] op_sel_hi:[1,1,0]
	v_pk_fma_f32 v[50:51], v[64:65], v[64:65], v[58:59] op_sel_hi:[1,1,0]
	v_pk_add_f32 v[38:39], v[40:41], v[40:41] op_sel:[0,1] op_sel_hi:[1,0]
	v_pk_add_f32 v[8:9], v[8:9], v[8:9] op_sel:[0,1] op_sel_hi:[1,0]
	v_mov_b32_e32 v49, v69
	v_mov_b32_e32 v51, v70
	v_mov_b32_e32 v39, v59
	v_mov_b32_e32 v9, v57
	v_pk_add_f32 v[40:41], v[48:49], v[50:51]
	v_pk_add_f32 v[8:9], v[8:9], v[38:39]
	v_pk_add_f32 v[8:9], v[8:9], v[40:41]
	v_add_f32_e32 v8, v8, v9
	v_mov_b32_e32 v75, v8
	s_waitcnt vmcnt(0)
; __device__ __forceinline__ float wave_sum(float v) {
; #pragma unroll
;     for (int o = 1; o < 64; o <<= 1) v += __shfl_xor(v, o);
;     return v;
; }
; __device__ __forceinline__ void pool_phase(const float* __restrict__ x, const bf16_t* __restrict__ x16, const float* __restrict__ g, const float* rsq, bf16_t* __restrict__ pooled, LAS unsigned char* lds, int tid, int wid, int lane, int bid) {
;     ...
;                 for (int j = 0; j < 8; ++j) { const f32x4 v = xr[lane + 64 * j]; s += (v[0] * v[0] + v[1] * v[1]) + (v[2] * v[2] + v[3] * v[3]); }
;                 val = 1.0f / sqrtf(wave_sum(s) * (1.0f / DM) + RMS_EPS); }
	v_mov_b32_e32 v18, v216
	v_mov_b32_e32 v19, v217
	v_mov_b32_e32 v20, v218
	v_mov_b32_e32 v21, v219
	v_mov_b32_e32 v38, v220
	v_mov_b32_e32 v39, v221
	v_mov_b32_e32 v40, v222
	v_mov_b32_e32 v41, v223
	v_mov_b32_e32 v42, v224
	v_mov_b32_e32 v43, v225
	v_mov_b32_e32 v44, v226
	v_mov_b32_e32 v45, v227
	v_mov_b32_e32 v46, v228
	v_mov_b32_e32 v47, v229
	v_mov_b32_e32 v48, v230
	v_mov_b32_e32 v49, v231
	v_mov_b32_e32 v50, v232
	v_mov_b32_e32 v51, v233
	v_mov_b32_e32 v52, v234
	v_mov_b32_e32 v53, v235
	v_mov_b32_e32 v54, v236
	v_mov_b32_e32 v55, v237
	v_mov_b32_e32 v56, v238
	v_mov_b32_e32 v57, v239
	v_mov_b32_e32 v58, v240
	v_mov_b32_e32 v59, v241
	v_mov_b32_e32 v60, v242
	v_mov_b32_e32 v61, v243
	v_mov_b32_e32 v62, v244
	v_mov_b32_e32 v63, v245
	v_mov_b32_e32 v64, v246
	v_mov_b32_e32 v65, v247
	v_mov_b32_e32 v8, v18
	v_mov_b32_e32 v9, v38
	v_mov_b32_e32 v38, v19
	v_mov_b32_e32 v19, v40
	v_mov_b32_e32 v40, v21
	v_mov_b32_e32 v18, v20
	v_pk_mul_f32 v[20:21], v[44:45], v[44:45]
	v_pk_mul_f32 v[42:43], v[42:43], v[42:43]
	v_pk_mul_f32 v[38:39], v[38:39], v[38:39]
	v_pk_mul_f32 v[40:41], v[40:41], v[40:41]
	v_mul_f32_e32 v69, v60, v60
	v_mul_f32_e32 v70, v61, v61
	v_pk_mov_b32 v[60:61], v[42:43], v[20:21] op_sel:[1,0]
	v_mov_b32_e32 v43, v21
	v_pk_fma_f32 v[8:9], v[8:9], v[8:9], v[38:39]
	v_pk_fma_f32 v[18:19], v[18:19], v[18:19], v[40:41]
	v_mul_f32_e32 v37, v46, v46
	v_mul_f32_e32 v44, v51, v51
	v_mul_f32_e32 v46, v53, v53
	v_pk_add_f32 v[38:39], v[60:61], v[42:43]
	v_pk_add_f32 v[8:9], v[8:9], v[18:19]
	v_mul_f32_e32 v66, v47, v47
	v_mul_f32_e32 v67, v48, v48
	v_mul_f32_e32 v68, v49, v49
	v_pk_fma_f32 v[20:21], v[50:51], v[50:51], v[44:45] op_sel_hi:[1,1,0]
	v_pk_fma_f32 v[44:45], v[52:53], v[52:53], v[46:47] op_sel_hi:[1,1,0]
	v_pk_add_f32 v[18:19], v[38:39], v[38:39] op_sel:[0,1] op_sel_hi:[1,0]
	v_pk_add_f32 v[8:9], v[8:9], v[8:9] op_sel:[0,1] op_sel_hi:[1,0]
	v_pk_mul_f32 v[48:49], v[56:57], v[56:57]
	v_pk_mul_f32 v[54:55], v[54:55], v[54:55]
	v_mov_b32_e32 v21, v67
	v_mov_b32_e32 v45, v68
	v_mov_b32_e32 v19, v66
	v_mov_b32_e32 v9, v37
	v_pk_mov_b32 v[46:47], v[54:55], v[48:49] op_sel:[1,0]
	v_mov_b32_e32 v55, v49
	v_pk_add_f32 v[20:21], v[20:21], v[44:45]
	v_pk_add_f32 v[8:9], v[8:9], v[18:19]
	v_mul_f32_e32 v57, v58, v58
	v_mul_f32_e32 v59, v59, v59
	v_mul_f32_e32 v56, v63, v63
	v_mul_f32_e32 v58, v65, v65
	v_pk_add_f32 v[40:41], v[46:47], v[54:55]
	v_pk_add_f32 v[8:9], v[8:9], v[20:21]
	v_pk_fma_f32 v[48:49], v[62:63], v[62:63], v[56:57] op_sel_hi:[1,1,0]
	v_pk_fma_f32 v[50:51], v[64:65], v[64:65], v[58:59] op_sel_hi:[1,1,0]
	v_pk_add_f32 v[38:39], v[40:41], v[40:41] op_sel:[0,1] op_sel_hi:[1,0]
	v_pk_add_f32 v[8:9], v[8:9], v[8:9] op_sel:[0,1] op_sel_hi:[1,0]
	v_mov_b32_e32 v49, v69
	v_mov_b32_e32 v51, v70
	v_mov_b32_e32 v39, v59
	v_mov_b32_e32 v9, v57
	v_pk_add_f32 v[40:41], v[48:49], v[50:51]
	v_pk_add_f32 v[8:9], v[8:9], v[38:39]
	v_pk_add_f32 v[8:9], v[8:9], v[40:41]
	v_add_f32_e32 v8, v8, v9
	v_mov_b32_e32 v76, v8
	ds_bpermute_b32 v248, v77, v71
	ds_bpermute_b32 v249, v77, v72
	ds_bpermute_b32 v250, v77, v73
	ds_bpermute_b32 v251, v77, v74
	ds_bpermute_b32 v252, v77, v75
	ds_bpermute_b32 v253, v77, v76
	s_waitcnt lgkmcnt(0)
	v_add_f32_e32 v71, v71, v248
	v_add_f32_e32 v72, v72, v249
	v_add_f32_e32 v73, v73, v250
	v_add_f32_e32 v74, v74, v251
	v_add_f32_e32 v75, v75, v252
	v_add_f32_e32 v76, v76, v253
	ds_bpermute_b32 v248, v78, v71
	ds_bpermute_b32 v249, v78, v72
	ds_bpermute_b32 v250, v78, v73
	ds_bpermute_b32 v251, v78, v74
	ds_bpermute_b32 v252, v78, v75
	ds_bpermute_b32 v253, v78, v76
	s_waitcnt lgkmcnt(0)
	v_add_f32_e32 v71, v71, v248
	v_add_f32_e32 v72, v72, v249
	v_add_f32_e32 v73, v73, v250
	v_add_f32_e32 v74, v74, v251
	v_add_f32_e32 v75, v75, v252
	v_add_f32_e32 v76, v76, v253
	ds_bpermute_b32 v248, v79, v71
	ds_bpermute_b32 v249, v79, v72
	ds_bpermute_b32 v250, v79, v73
	ds_bpermute_b32 v251, v79, v74
	ds_bpermute_b32 v252, v79, v75
	ds_bpermute_b32 v253, v79, v76
	s_waitcnt lgkmcnt(0)
	v_add_f32_e32 v71, v71, v248
	v_add_f32_e32 v72, v72, v249
	v_add_f32_e32 v73, v73, v250
	v_add_f32_e32 v74, v74, v251
	v_add_f32_e32 v75, v75, v252
	v_add_f32_e32 v76, v76, v253
	ds_bpermute_b32 v248, v82, v71
	ds_bpermute_b32 v249, v82, v72
	ds_bpermute_b32 v250, v82, v73
	ds_bpermute_b32 v251, v82, v74
	ds_bpermute_b32 v252, v82, v75
	ds_bpermute_b32 v253, v82, v76
	s_waitcnt lgkmcnt(0)
	v_add_f32_e32 v71, v71, v248
	v_add_f32_e32 v72, v72, v249
	v_add_f32_e32 v73, v73, v250
	v_add_f32_e32 v74, v74, v251
	v_add_f32_e32 v75, v75, v252
	v_add_f32_e32 v76, v76, v253
	ds_bpermute_b32 v248, v83, v71
	ds_bpermute_b32 v249, v83, v72
	ds_bpermute_b32 v250, v83, v73
	ds_bpermute_b32 v251, v83, v74
	ds_bpermute_b32 v252, v83, v75
	ds_bpermute_b32 v253, v83, v76
	s_waitcnt lgkmcnt(0)
	v_add_f32_e32 v71, v71, v248
	v_add_f32_e32 v72, v72, v249
	v_add_f32_e32 v73, v73, v250
	v_add_f32_e32 v74, v74, v251
	v_add_f32_e32 v75, v75, v252
	v_add_f32_e32 v76, v76, v253
	ds_bpermute_b32 v248, v206, v71
	ds_bpermute_b32 v249, v206, v72
	ds_bpermute_b32 v250, v206, v73
	ds_bpermute_b32 v251, v206, v74
	ds_bpermute_b32 v252, v206, v75
	ds_bpermute_b32 v253, v206, v76
	s_waitcnt lgkmcnt(0)
; __device__ __forceinline__ float rstd_of(float ssq) { return __builtin_amdgcn_rsqf(ssq * (1.0f / DM) + RMS_EPS); }
; __device__ __forceinline__ void pool_phase(const float* __restrict__ x, const bf16_t* __restrict__ x16, const float* __restrict__ g, const float* rsq, bf16_t* __restrict__ pooled, LAS unsigned char* lds, int tid, int wid, int lane, int bid) {
;     ...
;         for (int i = wid; i < 47; i += NWAVE) { const int r = t0 - 15 + i; float val = 0.f;
;             if (r >= bstart && rsq) val = rstd_of(wave_sum(lane < 32 ? rsq[(size_t)r * 64 + lane] : 0.f));
;             else if (r >= bstart) { float s = 0.f; const f32x4* xr = (const f32x4*)(x + (size_t)r * DM);
; #pragma unroll
;                 for (int j = 0; j < 8; ++j) { const f32x4 v = xr[lane + 64 * j]; s += (v[0] * v[0] + v[1] * v[1]) + (v[2] * v[2] + v[3] * v[3]); }
;                 val = 1.0f / sqrtf(wave_sum(s) * (1.0f / DM) + RMS_EPS); }
;             if (lane == 0) rs[i] = val; }
	v_add_f32_e32 v71, v71, v248
	v_add_f32_e32 v72, v72, v249
	v_add_f32_e32 v73, v73, v250
	v_add_f32_e32 v74, v74, v251
	v_add_f32_e32 v75, v75, v252
	v_add_f32_e32 v76, v76, v253
	v_mov_b32_e32 v5, v71
	v_fmamk_f32 v5, v5, 0x3a000000, v27
	v_mul_f32_e32 v8, 0x4f800000, v5
	v_cmp_gt_f32_e32 vcc, s41, v5
	s_nop 1
	v_cndmask_b32_e32 v5, v5, v8, vcc
	v_sqrt_f32_e32 v8, v5
	s_nop 0
	v_add_u32_e32 v9, -1, v8
	v_add_u32_e32 v18, 1, v8
	v_fma_f32 v19, -v9, v8, v5
	v_fma_f32 v20, -v18, v8, v5
	v_cmp_ge_f32_e64 s[12:13], 0, v19
	s_nop 1
	v_cndmask_b32_e64 v8, v8, v9, s[12:13]
	v_cmp_lt_f32_e64 s[12:13], 0, v20
	s_nop 1
	v_cndmask_b32_e64 v8, v8, v18, s[12:13]
	v_mul_f32_e32 v9, 0x37800000, v8
	v_cndmask_b32_e32 v8, v8, v9, vcc
	v_cmp_class_f32_e32 vcc, v5, v28
	s_nop 1
	v_cndmask_b32_e32 v5, v8, v5, vcc
	v_div_scale_f32 v8, s[12:13], v5, v5, 1.0
	v_rcp_f32_e32 v9, v8
	v_div_scale_f32 v18, vcc, 1.0, v5, 1.0
	v_fma_f32 v19, -v8, v9, 1.0
	v_fmac_f32_e32 v9, v19, v9
	v_mul_f32_e32 v19, v18, v9
	v_fma_f32 v20, -v8, v19, v18
	v_fmac_f32_e32 v19, v20, v9
	v_fma_f32 v8, -v8, v19, v18
	v_div_fmas_f32 v8, v8, v9, v19
	v_div_fixup_f32 v5, v8, v5, 1.0
	v_mov_b32_e32 v71, v5
	v_mov_b32_e32 v5, v72
	v_fmamk_f32 v5, v5, 0x3a000000, v27
	v_mul_f32_e32 v8, 0x4f800000, v5
	v_cmp_gt_f32_e32 vcc, s41, v5
	s_nop 1
	v_cndmask_b32_e32 v5, v5, v8, vcc
	v_sqrt_f32_e32 v8, v5
	s_nop 0
	v_add_u32_e32 v9, -1, v8
	v_add_u32_e32 v18, 1, v8
	v_fma_f32 v19, -v9, v8, v5
	v_fma_f32 v20, -v18, v8, v5
	v_cmp_ge_f32_e64 s[12:13], 0, v19
	s_nop 1
	v_cndmask_b32_e64 v8, v8, v9, s[12:13]
	v_cmp_lt_f32_e64 s[12:13], 0, v20
	s_nop 1
	v_cndmask_b32_e64 v8, v8, v18, s[12:13]
	v_mul_f32_e32 v9, 0x37800000, v8
	v_cndmask_b32_e32 v8, v8, v9, vcc
	v_cmp_class_f32_e32 vcc, v5, v28
	s_nop 1
	v_cndmask_b32_e32 v5, v8, v5, vcc
	v_div_scale_f32 v8, s[12:13], v5, v5, 1.0
	v_rcp_f32_e32 v9, v8
	v_div_scale_f32 v18, vcc, 1.0, v5, 1.0
	v_fma_f32 v19, -v8, v9, 1.0
	v_fmac_f32_e32 v9, v19, v9
	v_mul_f32_e32 v19, v18, v9
	v_fma_f32 v20, -v8, v19, v18
	v_fmac_f32_e32 v19, v20, v9
	v_fma_f32 v8, -v8, v19, v18
	v_div_fmas_f32 v8, v8, v9, v19
	v_div_fixup_f32 v5, v8, v5, 1.0
	v_mov_b32_e32 v72, v5
	v_mov_b32_e32 v5, v73
	v_fmamk_f32 v5, v5, 0x3a000000, v27
	v_mul_f32_e32 v8, 0x4f800000, v5
	v_cmp_gt_f32_e32 vcc, s41, v5
	s_nop 1
	v_cndmask_b32_e32 v5, v5, v8, vcc
	v_sqrt_f32_e32 v8, v5
	s_nop 0
	v_add_u32_e32 v9, -1, v8
	v_add_u32_e32 v18, 1, v8
	v_fma_f32 v19, -v9, v8, v5
	v_fma_f32 v20, -v18, v8, v5
	v_cmp_ge_f32_e64 s[12:13], 0, v19
	s_nop 1
	v_cndmask_b32_e64 v8, v8, v9, s[12:13]
	v_cmp_lt_f32_e64 s[12:13], 0, v20
	s_nop 1
	v_cndmask_b32_e64 v8, v8, v18, s[12:13]
	v_mul_f32_e32 v9, 0x37800000, v8
	v_cndmask_b32_e32 v8, v8, v9, vcc
	v_cmp_class_f32_e32 vcc, v5, v28
	s_nop 1
	v_cndmask_b32_e32 v5, v8, v5, vcc
	v_div_scale_f32 v8, s[12:13], v5, v5, 1.0
	v_rcp_f32_e32 v9, v8
	v_div_scale_f32 v18, vcc, 1.0, v5, 1.0
	v_fma_f32 v19, -v8, v9, 1.0
	v_fmac_f32_e32 v9, v19, v9
	v_mul_f32_e32 v19, v18, v9
	v_fma_f32 v20, -v8, v19, v18
	v_fmac_f32_e32 v19, v20, v9
	v_fma_f32 v8, -v8, v19, v18
	v_div_fmas_f32 v8, v8, v9, v19
	v_div_fixup_f32 v5, v8, v5, 1.0
	v_mov_b32_e32 v73, v5
	v_mov_b32_e32 v5, v74
	v_fmamk_f32 v5, v5, 0x3a000000, v27
	v_mul_f32_e32 v8, 0x4f800000, v5
	v_cmp_gt_f32_e32 vcc, s41, v5
	s_nop 1
	v_cndmask_b32_e32 v5, v5, v8, vcc
	v_sqrt_f32_e32 v8, v5
	s_nop 0
	v_add_u32_e32 v9, -1, v8
	v_add_u32_e32 v18, 1, v8
	v_fma_f32 v19, -v9, v8, v5
	v_fma_f32 v20, -v18, v8, v5
	v_cmp_ge_f32_e64 s[12:13], 0, v19
	s_nop 1
	v_cndmask_b32_e64 v8, v8, v9, s[12:13]
	v_cmp_lt_f32_e64 s[12:13], 0, v20
	s_nop 1
	v_cndmask_b32_e64 v8, v8, v18, s[12:13]
	v_mul_f32_e32 v9, 0x37800000, v8
	v_cndmask_b32_e32 v8, v8, v9, vcc
	v_cmp_class_f32_e32 vcc, v5, v28
	s_nop 1
	v_cndmask_b32_e32 v5, v8, v5, vcc
	v_div_scale_f32 v8, s[12:13], v5, v5, 1.0
	v_rcp_f32_e32 v9, v8
	v_div_scale_f32 v18, vcc, 1.0, v5, 1.0
	v_fma_f32 v19, -v8, v9, 1.0
	v_fmac_f32_e32 v9, v19, v9
	v_mul_f32_e32 v19, v18, v9
	v_fma_f32 v20, -v8, v19, v18
	v_fmac_f32_e32 v19, v20, v9
	v_fma_f32 v8, -v8, v19, v18
	v_div_fmas_f32 v8, v8, v9, v19
	v_div_fixup_f32 v5, v8, v5, 1.0
	v_mov_b32_e32 v74, v5
	v_mov_b32_e32 v5, v75
	v_fmamk_f32 v5, v5, 0x3a000000, v27
	v_mul_f32_e32 v8, 0x4f800000, v5
	v_cmp_gt_f32_e32 vcc, s41, v5
	s_nop 1
	v_cndmask_b32_e32 v5, v5, v8, vcc
	v_sqrt_f32_e32 v8, v5
	s_nop 0
	v_add_u32_e32 v9, -1, v8
	v_add_u32_e32 v18, 1, v8
	v_fma_f32 v19, -v9, v8, v5
	v_fma_f32 v20, -v18, v8, v5
	v_cmp_ge_f32_e64 s[12:13], 0, v19
	s_nop 1
	v_cndmask_b32_e64 v8, v8, v9, s[12:13]
	v_cmp_lt_f32_e64 s[12:13], 0, v20
	s_nop 1
	v_cndmask_b32_e64 v8, v8, v18, s[12:13]
	v_mul_f32_e32 v9, 0x37800000, v8
	v_cndmask_b32_e32 v8, v8, v9, vcc
	v_cmp_class_f32_e32 vcc, v5, v28
	s_nop 1
	v_cndmask_b32_e32 v5, v8, v5, vcc
	v_div_scale_f32 v8, s[12:13], v5, v5, 1.0
	v_rcp_f32_e32 v9, v8
	v_div_scale_f32 v18, vcc, 1.0, v5, 1.0
	v_fma_f32 v19, -v8, v9, 1.0
	v_fmac_f32_e32 v9, v19, v9
	v_mul_f32_e32 v19, v18, v9
	v_fma_f32 v20, -v8, v19, v18
	v_fmac_f32_e32 v19, v20, v9
	v_fma_f32 v8, -v8, v19, v18
	v_div_fmas_f32 v8, v8, v9, v19
	v_div_fixup_f32 v5, v8, v5, 1.0
	v_mov_b32_e32 v75, v5
	v_mov_b32_e32 v5, v76
	v_fmamk_f32 v5, v5, 0x3a000000, v27
	v_mul_f32_e32 v8, 0x4f800000, v5
	v_cmp_gt_f32_e32 vcc, s41, v5
	s_nop 1
	v_cndmask_b32_e32 v5, v5, v8, vcc
	v_sqrt_f32_e32 v8, v5
	s_nop 0
	v_add_u32_e32 v9, -1, v8
	v_add_u32_e32 v18, 1, v8
	v_fma_f32 v19, -v9, v8, v5
	v_fma_f32 v20, -v18, v8, v5
	v_cmp_ge_f32_e64 s[12:13], 0, v19
	s_nop 1
	v_cndmask_b32_e64 v8, v8, v9, s[12:13]
	v_cmp_lt_f32_e64 s[12:13], 0, v20
	s_nop 1
	v_cndmask_b32_e64 v8, v8, v18, s[12:13]
	v_mul_f32_e32 v9, 0x37800000, v8
	v_cndmask_b32_e32 v8, v8, v9, vcc
	v_cmp_class_f32_e32 vcc, v5, v28
	s_nop 1
	v_cndmask_b32_e32 v5, v8, v5, vcc
	v_div_scale_f32 v8, s[12:13], v5, v5, 1.0
	v_rcp_f32_e32 v9, v8
	v_div_scale_f32 v18, vcc, 1.0, v5, 1.0
	v_fma_f32 v19, -v8, v9, 1.0
	v_fmac_f32_e32 v9, v19, v9
	v_mul_f32_e32 v19, v18, v9
	v_fma_f32 v20, -v8, v19, v18
	v_fmac_f32_e32 v19, v20, v9
	v_fma_f32 v8, -v8, v19, v18
	v_div_fmas_f32 v8, v8, v9, v19
	v_div_fixup_f32 v5, v8, v5, 1.0
	v_mov_b32_e32 v76, v5
	s_add_i32 s15, s16, 0
	s_cmp_lt_i32 s15, s44
	s_cbranch_scc0 .LplA_s1_z0
	v_mov_b32_e32 v71, 0
; __device__ __forceinline__ void pool_phase(const float* __restrict__ x, const bf16_t* __restrict__ x16, const float* __restrict__ g, const float* rsq, bf16_t* __restrict__ pooled, LAS unsigned char* lds, int tid, int wid, int lane, int bid) {
;     ...
;             if (lane == 0) rs[i] = val; }
;         __syncthreads();
;         const int c = tid * 4, w = 2 << (c >> 9);
;         const f32x4 gv = *(const f32x4*)(g + c);
;         f32x4 S = {0.f, 0.f, 0.f, 0.f};
;         for (int j = 1; j < w; ++j) { const int r = t0 - j; if (r >= bstart) S += ldx4(x, x16, (size_t)r * DM + c) * rs[15 - j]; }
;         for (int tt = 0; tt < 32; ++tt) { const int r = t0 + tt;
;             const f32x4 h = ldx4(x, x16, (size_t)r * DM + c) * rs[15 + tt];
.LplA_s1_z0:
	s_add_i32 s15, s16, 8
	s_cmp_lt_i32 s15, s44
	s_cbranch_scc0 .LplA_s1_z1
	v_mov_b32_e32 v72, 0
.LplA_s1_z1:
	s_add_i32 s15, s16, 16
	s_cmp_lt_i32 s15, s44
	s_cbranch_scc0 .LplA_s1_z2
	v_mov_b32_e32 v73, 0
.LplA_s1_z2:
	s_add_i32 s15, s16, 24
	s_cmp_lt_i32 s15, s44
	s_cbranch_scc0 .LplA_s1_z3
	v_mov_b32_e32 v74, 0
.LplA_s1_z3:
	s_add_i32 s15, s16, 32
	s_cmp_lt_i32 s15, s44
	s_cbranch_scc0 .LplA_s1_z4
	v_mov_b32_e32 v75, 0
.LplA_s1_z4:
	s_add_i32 s15, s16, 40
	s_cmp_lt_i32 s15, s44
	s_cbranch_scc0 .LplA_s1_z5
	v_mov_b32_e32 v76, 0
.LplA_s1_z5:
	s_mov_b64 exec, s[4:5]
	v_mov_b32_e32 v66, s38
	ds_write_b32 v66, v71 offset:0
	ds_write_b32 v66, v72 offset:32
	ds_write_b32 v66, v73 offset:64
	ds_write_b32 v66, v74 offset:96
	ds_write_b32 v66, v75 offset:128
	s_cmp_gt_i32 s33, 6
	s_cbranch_scc1 .LplA_s1_done
	ds_write_b32 v66, v76 offset:160
.LplA_s1_done:
	s_mov_b64 exec, -1
.LBB0_77:
	v_mov_b32_e32 v6, v4
	v_mov_b32_e32 v7, v4
	v_mov_b32_e32 v5, v4
	v_mov_b64_e32 v[8:9], v[6:7]
	v_mov_b64_e32 v[6:7], v[4:5]
	s_waitcnt lgkmcnt(0)
	s_barrier
	v_readfirstlane_b32 s15, v22
	v_lshlrev_b32_e32 v66, 2, v29
	v_min_u32_e32 v66, 0xb8, v66
	ds_read_b32 v37, v66
	s_mov_b32 s13, 0
	s_mov_b32 s17, s14
	s_sub_i32 s31, s14, s44
	s_sub_i32 s28, s14, s15
	s_add_i32 s28, s28, 1
	s_sub_i32 s30, 16, s15
	s_mov_b32 s29, 15
	v_mov_b32_e32 v40, 0
	v_mov_b32_e32 v41, 0
	v_mov_b32_e32 v42, 0
	v_mov_b32_e32 v43, 0
	s_sub_i32 s34, s14, 1
	s_max_i32 s34, s34, s44
	s_lshl_b32 s12, s34, 13
	v_lshl_add_u64 v[60:61], v[12:13], 0, s[12:13]
	global_load_dwordx4 v[148:151], v[60:61], off
	s_sub_i32 s34, s14, 2
	s_max_i32 s34, s34, s44
	s_lshl_b32 s12, s34, 13
	v_lshl_add_u64 v[60:61], v[12:13], 0, s[12:13]
	global_load_dwordx4 v[152:155], v[60:61], off
	s_sub_i32 s34, s14, 3
	s_max_i32 s34, s34, s44
	s_lshl_b32 s12, s34, 13
	v_lshl_add_u64 v[60:61], v[12:13], 0, s[12:13]
	global_load_dwordx4 v[156:159], v[60:61], off
	s_sub_i32 s34, s14, 4
	s_max_i32 s34, s34, s44
	s_lshl_b32 s12, s34, 13
	v_lshl_add_u64 v[60:61], v[12:13], 0, s[12:13]
	global_load_dwordx4 v[160:163], v[60:61], off
	s_sub_i32 s34, s14, 5
	s_max_i32 s34, s34, s44
	s_lshl_b32 s12, s34, 13
	v_lshl_add_u64 v[60:61], v[12:13], 0, s[12:13]
	global_load_dwordx4 v[164:167], v[60:61], off
	s_sub_i32 s34, s14, 6
	s_max_i32 s34, s34, s44
	s_lshl_b32 s12, s34, 13
	v_lshl_add_u64 v[60:61], v[12:13], 0, s[12:13]
	global_load_dwordx4 v[168:171], v[60:61], off
	s_sub_i32 s34, s14, 7
	s_max_i32 s34, s34, s44
	s_lshl_b32 s12, s34, 13
	v_lshl_add_u64 v[60:61], v[12:13], 0, s[12:13]
	global_load_dwordx4 v[172:175], v[60:61], off
	s_sub_i32 s34, s14, 8
	s_max_i32 s34, s34, s44
	s_lshl_b32 s12, s34, 13
	v_lshl_add_u64 v[60:61], v[12:13], 0, s[12:13]
	global_load_dwordx4 v[176:179], v[60:61], off
	s_sub_i32 s34, s14, 9
	s_max_i32 s34, s34, s44
	s_lshl_b32 s12, s34, 13
	v_lshl_add_u64 v[60:61], v[12:13], 0, s[12:13]
	global_load_dwordx4 v[180:183], v[60:61], off
	s_sub_i32 s34, s14, 10
	s_max_i32 s34, s34, s44
	s_lshl_b32 s12, s34, 13
	v_lshl_add_u64 v[60:61], v[12:13], 0, s[12:13]
	global_load_dwordx4 v[184:187], v[60:61], off
	s_sub_i32 s34, s14, 11
	s_max_i32 s34, s34, s44
	s_lshl_b32 s12, s34, 13
	v_lshl_add_u64 v[60:61], v[12:13], 0, s[12:13]
	global_load_dwordx4 v[188:191], v[60:61], off
	s_sub_i32 s34, s14, 12
	s_max_i32 s34, s34, s44
	s_lshl_b32 s12, s34, 13
	v_lshl_add_u64 v[60:61], v[12:13], 0, s[12:13]
	global_load_dwordx4 v[192:195], v[60:61], off
	s_sub_i32 s34, s14, 13
	s_max_i32 s34, s34, s44
	s_lshl_b32 s12, s34, 13
	v_lshl_add_u64 v[60:61], v[12:13], 0, s[12:13]
	global_load_dwordx4 v[196:199], v[60:61], off
	s_sub_i32 s34, s14, 14
	s_max_i32 s34, s34, s44
	s_lshl_b32 s12, s34, 13
	v_lshl_add_u64 v[60:61], v[12:13], 0, s[12:13]
	global_load_dwordx4 v[200:203], v[60:61], off
	s_sub_i32 s34, s14, 15
	s_max_i32 s34, s34, s44
	s_lshl_b32 s12, s34, 13
	v_lshl_add_u64 v[60:61], v[12:13], 0, s[12:13]
	global_load_dwordx4 v[208:211], v[60:61], off
	s_add_i32 s34, s17, 0
	s_lshl_b32 s12, s34, 13
	v_lshl_add_u64 v[60:61], v[12:13], 0, s[12:13]
	global_load_dwordx4 v[84:87], v[60:61], off
	s_add_i32 s34, s28, 0
	s_max_i32 s34, s34, s44
	s_lshl_b32 s12, s34, 13
	v_lshl_add_u64 v[60:61], v[12:13], 0, s[12:13]
	global_load_dwordx4 v[88:91], v[60:61], off
	s_add_i32 s34, s17, 1
	s_lshl_b32 s12, s34, 13
	v_lshl_add_u64 v[60:61], v[12:13], 0, s[12:13]
	global_load_dwordx4 v[92:95], v[60:61], off
	s_add_i32 s34, s28, 1
	s_max_i32 s34, s34, s44
	s_lshl_b32 s12, s34, 13
	v_lshl_add_u64 v[60:61], v[12:13], 0, s[12:13]
	global_load_dwordx4 v[96:99], v[60:61], off
	s_add_i32 s34, s17, 2
	s_lshl_b32 s12, s34, 13
	v_lshl_add_u64 v[60:61], v[12:13], 0, s[12:13]
	global_load_dwordx4 v[100:103], v[60:61], off
	s_add_i32 s34, s28, 2
	s_max_i32 s34, s34, s44
	s_lshl_b32 s12, s34, 13
	v_lshl_add_u64 v[60:61], v[12:13], 0, s[12:13]
	global_load_dwordx4 v[104:107], v[60:61], off
	s_add_i32 s34, s17, 3
	s_lshl_b32 s12, s34, 13
	v_lshl_add_u64 v[60:61], v[12:13], 0, s[12:13]
	global_load_dwordx4 v[108:111], v[60:61], off
	s_add_i32 s34, s28, 3
	s_max_i32 s34, s34, s44
	s_lshl_b32 s12, s34, 13
	v_lshl_add_u64 v[60:61], v[12:13], 0, s[12:13]
	global_load_dwordx4 v[112:115], v[60:61], off
	s_add_i32 s34, s17, 4
	s_lshl_b32 s12, s34, 13
	v_lshl_add_u64 v[60:61], v[12:13], 0, s[12:13]
	global_load_dwordx4 v[116:119], v[60:61], off
	s_add_i32 s34, s28, 4
	s_max_i32 s34, s34, s44
	s_lshl_b32 s12, s34, 13
	v_lshl_add_u64 v[60:61], v[12:13], 0, s[12:13]
	global_load_dwordx4 v[120:123], v[60:61], off
	s_add_i32 s34, s17, 5
	s_lshl_b32 s12, s34, 13
	v_lshl_add_u64 v[60:61], v[12:13], 0, s[12:13]
	global_load_dwordx4 v[124:127], v[60:61], off
	s_add_i32 s34, s28, 5
	s_max_i32 s34, s34, s44
	s_lshl_b32 s12, s34, 13
	v_lshl_add_u64 v[60:61], v[12:13], 0, s[12:13]
	global_load_dwordx4 v[128:131], v[60:61], off
	s_add_i32 s34, s17, 6
	s_lshl_b32 s12, s34, 13
	v_lshl_add_u64 v[60:61], v[12:13], 0, s[12:13]
	global_load_dwordx4 v[132:135], v[60:61], off
	s_add_i32 s34, s28, 6
	s_max_i32 s34, s34, s44
	s_lshl_b32 s12, s34, 13
	v_lshl_add_u64 v[60:61], v[12:13], 0, s[12:13]
	global_load_dwordx4 v[136:139], v[60:61], off
	s_add_i32 s34, s17, 7
	s_lshl_b32 s12, s34, 13
	v_lshl_add_u64 v[60:61], v[12:13], 0, s[12:13]
	global_load_dwordx4 v[140:143], v[60:61], off
	s_add_i32 s34, s28, 7
	s_max_i32 s34, s34, s44
	s_lshl_b32 s12, s34, 13
	v_lshl_add_u64 v[60:61], v[12:13], 0, s[12:13]
	global_load_dwordx4 v[144:147], v[60:61], off
	s_waitcnt lgkmcnt(0)
	s_cmp_le_i32 s15, 1
	s_cbranch_scc1 .LplA_init_done
; __device__ __forceinline__ void pool_phase(const float* __restrict__ x, const bf16_t* __restrict__ x16, const float* __restrict__ g, const float* rsq, bf16_t* __restrict__ pooled, LAS unsigned char* lds, int tid, int wid, int lane, int bid) {
;     ...
;         const int c = tid * 4, w = 2 << (c >> 9);
;         const f32x4 gv = *(const f32x4*)(g + c);
;         f32x4 S = {0.f, 0.f, 0.f, 0.f};
;         for (int j = 1; j < w; ++j) { const int r = t0 - j; if (r >= bstart) S += ldx4(x, x16, (size_t)r * DM + c) * rs[15 - j]; }
	s_sub_i32 s34, s14, 1
	s_cmp_lt_i32 s34, s44
	s_cbranch_scc1 .LplA_init_done
	v_readlane_b32 s35, v37, 14
	s_waitcnt vmcnt(30)
	s_nop 1
	v_fma_f32 v40, v148, s35, v40
	v_fma_f32 v41, v149, s35, v41
	v_fma_f32 v42, v150, s35, v42
	v_fma_f32 v43, v151, s35, v43
	s_cmp_le_i32 s15, 2
	s_cbranch_scc1 .LplA_init_done
	s_sub_i32 s34, s14, 2
	s_cmp_lt_i32 s34, s44
	s_cbranch_scc1 .LplA_init_done
	v_readlane_b32 s35, v37, 13
	s_waitcnt vmcnt(29)
	s_nop 1
	v_fma_f32 v40, v152, s35, v40
	v_fma_f32 v41, v153, s35, v41
	v_fma_f32 v42, v154, s35, v42
	v_fma_f32 v43, v155, s35, v43
	s_cmp_le_i32 s15, 3
	s_cbranch_scc1 .LplA_init_done
	s_sub_i32 s34, s14, 3
	s_cmp_lt_i32 s34, s44
	s_cbranch_scc1 .LplA_init_done
	v_readlane_b32 s35, v37, 12
	s_waitcnt vmcnt(28)
	s_nop 1
	v_fma_f32 v40, v156, s35, v40
	v_fma_f32 v41, v157, s35, v41
	v_fma_f32 v42, v158, s35, v42
	v_fma_f32 v43, v159, s35, v43
	s_cmp_le_i32 s15, 4
	s_cbranch_scc1 .LplA_init_done
	s_sub_i32 s34, s14, 4
	s_cmp_lt_i32 s34, s44
	s_cbranch_scc1 .LplA_init_done
	v_readlane_b32 s35, v37, 11
	s_waitcnt vmcnt(27)
	s_nop 1
	v_fma_f32 v40, v160, s35, v40
	v_fma_f32 v41, v161, s35, v41
	v_fma_f32 v42, v162, s35, v42
	v_fma_f32 v43, v163, s35, v43
	s_cmp_le_i32 s15, 5
	s_cbranch_scc1 .LplA_init_done
	s_sub_i32 s34, s14, 5
	s_cmp_lt_i32 s34, s44
	s_cbranch_scc1 .LplA_init_done
	v_readlane_b32 s35, v37, 10
	s_waitcnt vmcnt(26)
	s_nop 1
	v_fma_f32 v40, v164, s35, v40
	v_fma_f32 v41, v165, s35, v41
	v_fma_f32 v42, v166, s35, v42
	v_fma_f32 v43, v167, s35, v43
	s_cmp_le_i32 s15, 6
	s_cbranch_scc1 .LplA_init_done
	s_sub_i32 s34, s14, 6
	s_cmp_lt_i32 s34, s44
	s_cbranch_scc1 .LplA_init_done
	v_readlane_b32 s35, v37, 9
	s_waitcnt vmcnt(25)
	s_nop 1
	v_fma_f32 v40, v168, s35, v40
	v_fma_f32 v41, v169, s35, v41
	v_fma_f32 v42, v170, s35, v42
	v_fma_f32 v43, v171, s35, v43
	s_cmp_le_i32 s15, 7
	s_cbranch_scc1 .LplA_init_done
	s_sub_i32 s34, s14, 7
	s_cmp_lt_i32 s34, s44
	s_cbranch_scc1 .LplA_init_done
	v_readlane_b32 s35, v37, 8
	s_waitcnt vmcnt(24)
	s_nop 1
	v_fma_f32 v40, v172, s35, v40
	v_fma_f32 v41, v173, s35, v41
	v_fma_f32 v42, v174, s35, v42
	v_fma_f32 v43, v175, s35, v43
	s_cmp_le_i32 s15, 8
	s_cbranch_scc1 .LplA_init_done
	s_sub_i32 s34, s14, 8
	s_cmp_lt_i32 s34, s44
	s_cbranch_scc1 .LplA_init_done
	v_readlane_b32 s35, v37, 7
	s_waitcnt vmcnt(23)
	s_nop 1
	v_fma_f32 v40, v176, s35, v40
	v_fma_f32 v41, v177, s35, v41
	v_fma_f32 v42, v178, s35, v42
	v_fma_f32 v43, v179, s35, v43
	s_cmp_le_i32 s15, 9
	s_cbranch_scc1 .LplA_init_done
	s_sub_i32 s34, s14, 9
	s_cmp_lt_i32 s34, s44
	s_cbranch_scc1 .LplA_init_done
	v_readlane_b32 s35, v37, 6
	s_waitcnt vmcnt(22)
	s_nop 1
	v_fma_f32 v40, v180, s35, v40
	v_fma_f32 v41, v181, s35, v41
	v_fma_f32 v42, v182, s35, v42
	v_fma_f32 v43, v183, s35, v43
	s_cmp_le_i32 s15, 10
	s_cbranch_scc1 .LplA_init_done
	s_sub_i32 s34, s14, 10
	s_cmp_lt_i32 s34, s44
	s_cbranch_scc1 .LplA_init_done
	v_readlane_b32 s35, v37, 5
	s_waitcnt vmcnt(21)
	s_nop 1
	v_fma_f32 v40, v184, s35, v40
	v_fma_f32 v41, v185, s35, v41
	v_fma_f32 v42, v186, s35, v42
	v_fma_f32 v43, v187, s35, v43
	s_cmp_le_i32 s15, 11
	s_cbranch_scc1 .LplA_init_done
	s_sub_i32 s34, s14, 11
	s_cmp_lt_i32 s34, s44
	s_cbranch_scc1 .LplA_init_done
	v_readlane_b32 s35, v37, 4
	s_waitcnt vmcnt(20)
	s_nop 1
	v_fma_f32 v40, v188, s35, v40
	v_fma_f32 v41, v189, s35, v41
	v_fma_f32 v42, v190, s35, v42
	v_fma_f32 v43, v191, s35, v43
	s_cmp_le_i32 s15, 12
	s_cbranch_scc1 .LplA_init_done
	s_sub_i32 s34, s14, 12
	s_cmp_lt_i32 s34, s44
	s_cbranch_scc1 .LplA_init_done
	v_readlane_b32 s35, v37, 3
	s_waitcnt vmcnt(19)
	s_nop 1
	v_fma_f32 v40, v192, s35, v40
	v_fma_f32 v41, v193, s35, v41
	v_fma_f32 v42, v194, s35, v42
	v_fma_f32 v43, v195, s35, v43
	s_cmp_le_i32 s15, 13
	s_cbranch_scc1 .LplA_init_done
	s_sub_i32 s34, s14, 13
	s_cmp_lt_i32 s34, s44
	s_cbranch_scc1 .LplA_init_done
	v_readlane_b32 s35, v37, 2
	s_waitcnt vmcnt(18)
	s_nop 1
	v_fma_f32 v40, v196, s35, v40
	v_fma_f32 v41, v197, s35, v41
	v_fma_f32 v42, v198, s35, v42
	v_fma_f32 v43, v199, s35, v43
	s_cmp_le_i32 s15, 14
	s_cbranch_scc1 .LplA_init_done
	s_sub_i32 s34, s14, 14
	s_cmp_lt_i32 s34, s44
	s_cbranch_scc1 .LplA_init_done
	v_readlane_b32 s35, v37, 1
	s_waitcnt vmcnt(17)
	s_nop 1
	v_fma_f32 v40, v200, s35, v40
	v_fma_f32 v41, v201, s35, v41
	v_fma_f32 v42, v202, s35, v42
	v_fma_f32 v43, v203, s35, v43
	s_cmp_le_i32 s15, 15
	s_cbranch_scc1 .LplA_init_done
	s_sub_i32 s34, s14, 15
	s_cmp_lt_i32 s34, s44
	s_cbranch_scc1 .LplA_init_done
	v_readlane_b32 s35, v37, 0
	s_waitcnt vmcnt(16)
	s_nop 1
	v_fma_f32 v40, v208, s35, v40
	v_fma_f32 v41, v209, s35, v41
	v_fma_f32 v42, v210, s35, v42
	v_fma_f32 v43, v211, s35, v43
